# P5: odd-slot workgroups run the HBM-bound attention merge before their latency-bound GLU GEMM tiles (even-slot ones keep GLU first) so the two overlap across the grid
# baseline (speedup 1.0000x reference)
; #define TILE_LOOP(tile, N, C)                                                                                          \
;   for (int q0_ = (RBLK >> 3) * 2, tile = 0;                                                                            \
;        q0_ < (N) / 8 && ((tile = xcd_tile((q0_ + VHALF < (N) / 8 ? q0_ + VHALF : q0_), RBLK & 7, (C))), true);          \
;        q0_ += (RGRID >> 3) * 2)
; DI void phase5(const Params& P, char* smem) {
;   char* ws = P.ws;
;   const u16* Yb = (const u16*)(ws + OFF_YB); const u16* WgT = (const u16*)(ws + OFF_WGT);
;   u16* cat = (u16*)(ws + OFF_CAT);
;   TILE_LOOP(tile, 256 * 4, 4) {
;     const int brow = (tile >> 2) * 128, bcol = (tile & 3) * 128;
;     gemm_tile<true>(Yb + (long)brow * 512, 512, WgT + (long)bcol * 512, 512, 0, 8, 0, 0, smem, [&](int row, int col0, f32x4 v) {
;       const long r = brow + row; const int c = bcol + col0;
.LBB0_872:
	s_or_b64 exec, exec, s[0:1]
	s_mov_b32 s56, 0
	s_andn2_b64 vcc, exec, s[34:35]
	s_waitcnt lgkmcnt(0)
	s_barrier
	s_cbranch_vccnz .LBB0_875
	s_bitcmp1_b32 s74, 3
	s_cselect_b32 s56, 1, 0
	s_cmp_eq_u32 s56, 1
	s_cbranch_scc1 .LBB0_875
.Lp5_glu:
	s_lshl_b32 s0, s74, 5
	s_and_b32 s9, s0, 0x80
	s_lshl_b32 s0, s74, 7
	s_and_b32 s2, s0, 0x180
	s_lshl_b32 s0, s2, 10
	s_add_u32 s0, s78, s0
	s_addc_u32 s1, s79, 0
	v_xor_b32_e32 v1, v193, v189
	v_lshlrev_b32_e32 v0, 6, v189
	s_add_u32 s0, s0, 0x18a00000
	v_and_b32_e32 v0, 0x3e00, v0
	v_lshlrev_b32_e32 v1, 3, v1
	s_addc_u32 s1, s1, 0
	v_mov_b32_e32 v53, 0
	v_and_b32_e32 v2, 56, v1
	v_lshlrev_b32_e32 v52, 1, v0
	v_or_b32_e32 v1, 0x100, v191
	v_lshl_add_u64 v[4:5], s[0:1], 0, v[52:53]
	v_lshlrev_b32_e32 v52, 1, v2
	v_lshlrev_b32_e32 v3, 6, v1
	v_lshl_add_u64 v[54:55], v[4:5], 0, v[52:53]
	v_and_b32_e32 v4, 0x7e00, v3
	v_lshlrev_b32_e32 v6, 1, v4
	v_mov_b32_e32 v7, v53
	v_or_b32_e32 v3, 0x200, v191
	v_lshl_add_u64 v[6:7], s[0:1], 0, v[6:7]
	v_lshlrev_b32_e32 v5, 6, v3
	v_lshl_add_u64 v[56:57], v[6:7], 0, v[52:53]
	v_and_b32_e32 v6, 0xbe00, v5
	v_lshlrev_b32_e32 v8, 1, v6
	v_mov_b32_e32 v9, v53
	v_or_b32_e32 v5, 0x300, v189
	v_lshl_add_u64 v[8:9], s[0:1], 0, v[8:9]
	v_lshlrev_b32_e32 v7, 6, v5
	v_lshl_add_u64 v[58:59], v[8:9], 0, v[52:53]
	v_and_b32_e32 v8, 0xfe00, v7
	v_lshlrev_b32_e32 v10, 1, v8
	v_mov_b32_e32 v11, v53
	v_bitop3_b32 v7, v193, v170, 3 bitop3:0x6c
	v_lshl_add_u64 v[10:11], s[0:1], 0, v[10:11]
	v_and_or_b32 v134, v174, 64, v188
	v_lshl_add_u32 v135, v7, 4, v192
	v_or3_b32 v7, v124, v162, s2
	v_lshlrev_b32_e32 v1, 4, v1
	v_lshlrev_b32_e32 v3, 4, v3
	v_lshlrev_b32_e32 v5, 4, v5
	v_lshl_add_u64 v[60:61], v[10:11], 0, v[52:53]
	s_mov_b64 s[0:1], 0x80
	v_or_b32_e32 v138, 16, v134
	v_or_b32_e32 v140, 32, v134
	v_or_b32_e32 v142, 48, v134
	s_mov_b64 s[4:5], 0x100
	s_mov_b64 s[6:7], 0x180
	s_mov_b64 s[10:11], 0x200
	s_mov_b64 s[12:13], 0x280
	s_mov_b64 s[14:15], 0x300
	s_mov_b64 s[16:17], 0x380
	v_lshlrev_b32_e32 v52, 1, v7
	s_movk_i32 s8, 0x80
	v_lshl_add_u64 v[62:63], v[54:55], 0, s[0:1]
	v_lshl_add_u64 v[64:65], v[56:57], 0, s[0:1]
	v_lshl_add_u64 v[66:67], v[58:59], 0, s[0:1]
	v_lshl_add_u64 v[68:69], v[60:61], 0, s[0:1]
	v_lshlrev_b32_e32 v136, 7, v134
	v_and_b32_e32 v137, 0x2780, v171
	v_lshlrev_b32_e32 v139, 7, v138
	v_lshlrev_b32_e32 v141, 7, v140
	v_lshlrev_b32_e32 v143, 7, v142
	v_lshl_add_u32 v144, v173, 4, v192
	v_lshl_add_u64 v[70:71], v[54:55], 0, s[4:5]
	v_lshl_add_u64 v[72:73], v[56:57], 0, s[4:5]
	v_lshl_add_u64 v[74:75], v[58:59], 0, s[4:5]
	v_lshl_add_u64 v[76:77], v[60:61], 0, s[4:5]
	v_lshl_add_u64 v[78:79], v[54:55], 0, s[6:7]
	v_lshl_add_u64 v[80:81], v[56:57], 0, s[6:7]
	v_lshl_add_u64 v[82:83], v[58:59], 0, s[6:7]
	v_lshl_add_u64 v[84:85], v[60:61], 0, s[6:7]
	v_lshl_add_u64 v[86:87], v[54:55], 0, s[10:11]
	v_lshl_add_u64 v[88:89], v[56:57], 0, s[10:11]
	v_lshl_add_u64 v[90:91], v[58:59], 0, s[10:11]
	v_lshl_add_u64 v[92:93], v[60:61], 0, s[10:11]
	v_lshl_add_u64 v[94:95], v[54:55], 0, s[12:13]
	v_lshl_add_u64 v[96:97], v[56:57], 0, s[12:13]
	v_lshl_add_u64 v[98:99], v[58:59], 0, s[12:13]
	v_lshl_add_u64 v[100:101], v[60:61], 0, s[12:13]
	v_lshl_add_u64 v[102:103], v[54:55], 0, s[14:15]
	v_lshl_add_u64 v[104:105], v[56:57], 0, s[14:15]
	v_lshl_add_u64 v[106:107], v[58:59], 0, s[14:15]
	v_lshl_add_u64 v[108:109], v[60:61], 0, s[14:15]
	v_lshl_add_u64 v[110:111], v[54:55], 0, s[16:17]
	v_lshl_add_u64 v[112:113], v[56:57], 0, s[16:17]
	v_lshl_add_u64 v[114:115], v[58:59], 0, s[16:17]
	v_lshl_add_u64 v[116:117], v[60:61], 0, s[16:17]
	v_lshl_add_u64 v[118:119], s[54:55], 0, v[52:53]
	v_lshl_add_u64 v[120:121], s[62:63], 0, v[52:53]
	v_lshlrev_b32_e32 v52, 1, v0
	v_lshlrev_b32_e32 v122, 1, v2
	v_add_u32_e32 v145, v192, v168
	v_lshlrev_b32_e32 v124, 1, v4
	v_add_u32_e32 v146, v192, v1
	v_lshlrev_b32_e32 v126, 1, v6
	v_add_u32_e32 v147, v192, v3
	v_lshlrev_b32_e32 v130, 1, v8
	v_add_u32_e32 v148, v192, v5
	s_mov_b32 s18, s64

; DI unsigned pack2bf(float a, float b) { const f2_t v = {a, b}; return __builtin_bit_cast(unsigned, __builtin_convertvector(v, bf2_t)); }
; DI void phase5(const Params& P, char* smem) {
;     ...
;   const u16* Opart = (const u16*)(ws + OFF_OPART); const float* Lse = (const float*)(ws + OFF_LSE);
;   for (long idx = (long)VB * 256 + VT; idx < (long)NTOK * 64; idx += (long)NVB * 256) {
;     const int dg = (int)idx & 7, h = (int)(idx >> 3) & 7; const long tok = idx >> 6;
;     const int l = (int)(tok & 8191); const int ownb = l >> 8; const int nv = ownb < 3 ? ownb : 3;
;     const long base = (tok * 8 + h) * 4;
;     float ls[4]; float mx = -3e38f;
; #pragma unroll
;     for (int s = 0; s < 4; ++s) { const bool ok = (s == 3) || (s < nv); ls[s] = ok ? Lse[base + s] : -3e38f; mx = fmaxf(mx, ls[s]); }
;     float acc[8]; float wsum = 0.f;
; #pragma unroll
;     for (int k = 0; k < 8; ++k) acc[k] = 0.f;
; #pragma unroll
;     for (int s = 0; s < 4; ++s) {
;       const bool ok = (s == 3) || (s < nv);
;       if (ok) {
;         const float w = __expf(ls[s] - mx); wsum += w;
;         uint4 o = *reinterpret_cast<const uint4*>(Opart + (base + s) * 64 + dg * 8);
;         acc[0] += w * __uint_as_float(o.x << 16); acc[1] += w * __uint_as_float(o.x & 0xffff0000u);
;         acc[2] += w * __uint_as_float(o.y << 16); acc[3] += w * __uint_as_float(o.y & 0xffff0000u);
;         acc[4] += w * __uint_as_float(o.z << 16); acc[5] += w * __uint_as_float(o.z & 0xffff0000u);
;         acc[6] += w * __uint_as_float(o.w << 16); acc[7] += w * __uint_as_float(o.w & 0xffff0000u);
;       }
;     }
;     const float inv = 1.f / wsum;
;     *reinterpret_cast<uint4*>(cat + tok * 1024 + 512 + h * 64 + dg * 8) =
;         make_uint4(pack2bf(acc[0] * inv, acc[1] * inv), pack2bf(acc[2] * inv, acc[3] * inv), pack2bf(acc[4] * inv, acc[5] * inv), pack2bf(acc[6] * inv, acc[7] * inv));
;   }
.LBB0_875:
	s_cmp_eq_u32 s56, 2
	s_cbranch_scc1 .Lp5_end
	s_add_u32 s40, s78, 0x10000000
	s_mov_b64 s[0:1], 0x200000
	s_addc_u32 s41, s79, 0
	v_cmp_gt_i64_e32 vcc, s[0:1], v[128:129]
	s_and_saveexec_b64 s[10:11], vcc
	s_cbranch_execz .LBB0_892
	v_lshlrev_b32_e32 v0, 3, v189
	v_and_b32_e32 v2, 56, v0
	v_mov_b32_e32 v0, 0
	v_lshlrev_b32_e32 v4, 1, v2
	v_mov_b32_e32 v5, v0
	v_lshl_add_u64 v[4:5], s[78:79], 0, v[4:5]
	s_mov_b64 s[0:1], 0x8000000
	v_lshl_add_u64 v[10:11], v[4:5], 0, s[0:1]
	s_mov_b64 s[12:13], 0
	s_mov_b32 s2, 0xff61b1e6
	v_lshlrev_b32_e32 v12, 1, v2
	s_mov_b64 s[14:15], 0x1fffff
	v_mov_b64_e32 v[14:15], v[128:129]
	v_ashrrev_i64 v[16:17], 6, v[14:15]
	v_bfe_u32 v13, v14, 3, 3
	v_lshlrev_b64 v[20:21], 5, v[16:17]
	v_bfe_u32 v232, v16, 8, 5
	v_lshl_or_b32 v20, v13, 2, v20
	v_lshl_add_u64 v[22:23], v[20:21], 2, s[40:41]
	v_lshlrev_b64 v[18:19], 7, v[20:21]
	global_load_dwordx4 v[210:213], v[22:23], off
	v_lshl_add_u64 v[18:19], v[10:11], 0, v[18:19]
	global_load_dwordx4 v[214:217], v[18:19], off
	global_load_dwordx4 v[218:221], v[18:19], off offset:128
	global_load_dwordx4 v[222:225], v[18:19], off offset:256
	global_load_dwordx4 v[226:229], v[18:19], off offset:384
	v_lshlrev_b64 v[16:17], 11, v[16:17]
	v_lshlrev_b32_e32 v24, 7, v13
	v_mov_b32_e32 v25, v0
	v_lshl_add_u64 v[16:17], s[62:63], 0, v[16:17]
	v_mov_b32_e32 v13, v0
	v_lshl_add_u64 v[16:17], v[16:17], 0, v[24:25]
	v_lshl_add_u64 v[230:231], v[16:17], 0, v[12:13]
	v_lshl_add_u64 v[14:15], v[14:15], 0, s[66:67]
	s_mov_b32 s12, 7
	v_ashrrev_i64 v[16:17], 6, v[14:15]
	v_bfe_u32 v13, v14, 3, 3
	v_lshlrev_b64 v[20:21], 5, v[16:17]
	v_bfe_u32 v38, v16, 8, 5
	v_lshl_or_b32 v20, v13, 2, v20
	v_lshl_add_u64 v[22:23], v[20:21], 2, s[40:41]
	v_lshlrev_b64 v[18:19], 7, v[20:21]
	global_load_dwordx4 v[234:237], v[22:23], off
	v_lshl_add_u64 v[18:19], v[10:11], 0, v[18:19]
	global_load_dwordx4 v[238:241], v[18:19], off
	global_load_dwordx4 v[242:245], v[18:19], off offset:128
	global_load_dwordx4 v[246:249], v[18:19], off offset:256
	global_load_dwordx4 v[250:253], v[18:19], off offset:384
	v_lshlrev_b64 v[16:17], 11, v[16:17]
	v_lshlrev_b32_e32 v24, 7, v13
	v_mov_b32_e32 v25, v0
	v_lshl_add_u64 v[16:17], s[62:63], 0, v[16:17]
	v_mov_b32_e32 v13, v0
	v_lshl_add_u64 v[16:17], v[16:17], 0, v[24:25]
	v_lshl_add_u64 v[36:37], v[16:17], 0, v[12:13]
	v_lshl_add_u64 v[14:15], v[14:15], 0, s[66:67]
	s_waitcnt vmcnt(5)
	v_cmp_ne_u32_e64 s[4:5], 0, v232
	v_cmp_lt_u32_e64 s[6:7], 1, v232
	v_cmp_lt_u32_e64 s[8:9], 2, v232
	v_mov_b32_e32 v26, 0xff61b1e6
	v_cndmask_b32_e64 v27, v26, v210, s[4:5]
	v_cndmask_b32_e64 v28, v26, v211, s[6:7]
	v_cndmask_b32_e64 v29, v26, v212, s[8:9]
	v_max3_f32 v24, v27, s2, v28
	v_max3_f32 v24, v24, v29, v213
	v_sub_f32_e32 v1, v27, v24
	v_mul_f32_e32 v1, 0x3fb8aa3b, v1
	v_exp_f32_e32 v30, v1
	v_sub_f32_e32 v1, v28, v24
	v_mul_f32_e32 v1, 0x3fb8aa3b, v1
	v_exp_f32_e32 v32, v1
	v_sub_f32_e32 v1, v29, v24
	v_mul_f32_e32 v1, 0x3fb8aa3b, v1
	v_exp_f32_e32 v34, v1
	v_sub_f32_e32 v1, v213, v24
	v_mul_f32_e32 v1, 0x3fb8aa3b, v1
	v_exp_f32_e32 v48, v1
	v_cndmask_b32_e64 v214, 0, v214, s[4:5]
	v_cndmask_b32_e64 v215, 0, v215, s[4:5]
	v_cndmask_b32_e64 v216, 0, v216, s[4:5]
	v_cndmask_b32_e64 v217, 0, v217, s[4:5]
	v_cndmask_b32_e64 v218, 0, v218, s[6:7]
	v_cndmask_b32_e64 v219, 0, v219, s[6:7]
	v_cndmask_b32_e64 v220, 0, v220, s[6:7]
	v_cndmask_b32_e64 v221, 0, v221, s[6:7]
	v_cndmask_b32_e64 v222, 0, v222, s[8:9]
	v_cndmask_b32_e64 v223, 0, v223, s[8:9]
	v_cndmask_b32_e64 v224, 0, v224, s[8:9]
	v_cndmask_b32_e64 v225, 0, v225, s[8:9]
	v_add_f32_e32 v22, 0, v30
	v_add_f32_e32 v22, v32, v22
	v_add_f32_e32 v22, v34, v22
	v_add_f32_e32 v22, v48, v22
	v_lshlrev_b32_e32 v40, 16, v214
	v_and_b32_e32 v41, 0xffff0000, v214
	v_lshlrev_b32_e32 v42, 16, v215
	v_and_b32_e32 v43, 0xffff0000, v215
	v_lshlrev_b32_e32 v44, 16, v216
	v_and_b32_e32 v45, 0xffff0000, v216
	v_lshlrev_b32_e32 v46, 16, v217
	v_and_b32_e32 v47, 0xffff0000, v217
	v_pk_fma_f32 v[2:3], v[30:31], v[40:41], 0 op_sel_hi:[0,1,0]
	v_pk_fma_f32 v[4:5], v[30:31], v[42:43], 0 op_sel_hi:[0,1,0]
	v_pk_fma_f32 v[6:7], v[30:31], v[44:45], 0 op_sel_hi:[0,1,0]
	v_pk_fma_f32 v[8:9], v[30:31], v[46:47], 0 op_sel_hi:[0,1,0]
	v_lshlrev_b32_e32 v40, 16, v218
	v_and_b32_e32 v41, 0xffff0000, v218
	v_lshlrev_b32_e32 v42, 16, v219
	v_and_b32_e32 v43, 0xffff0000, v219
	v_lshlrev_b32_e32 v44, 16, v220
	v_and_b32_e32 v45, 0xffff0000, v220
	v_lshlrev_b32_e32 v46, 16, v221
	v_and_b32_e32 v47, 0xffff0000, v221
	v_pk_fma_f32 v[2:3], v[32:33], v[40:41], v[2:3] op_sel_hi:[0,1,1]
	v_pk_fma_f32 v[4:5], v[32:33], v[42:43], v[4:5] op_sel_hi:[0,1,1]
	v_pk_fma_f32 v[6:7], v[32:33], v[44:45], v[6:7] op_sel_hi:[0,1,1]
	v_pk_fma_f32 v[8:9], v[32:33], v[46:47], v[8:9] op_sel_hi:[0,1,1]
	v_lshlrev_b32_e32 v40, 16, v222
	v_and_b32_e32 v41, 0xffff0000, v222
	v_lshlrev_b32_e32 v42, 16, v223
	v_and_b32_e32 v43, 0xffff0000, v223
	v_lshlrev_b32_e32 v44, 16, v224
	v_and_b32_e32 v45, 0xffff0000, v224
	v_lshlrev_b32_e32 v46, 16, v225
	v_and_b32_e32 v47, 0xffff0000, v225
	v_pk_fma_f32 v[2:3], v[34:35], v[40:41], v[2:3] op_sel_hi:[0,1,1]
	v_pk_fma_f32 v[4:5], v[34:35], v[42:43], v[4:5] op_sel_hi:[0,1,1]
	v_pk_fma_f32 v[6:7], v[34:35], v[44:45], v[6:7] op_sel_hi:[0,1,1]
	v_pk_fma_f32 v[8:9], v[34:35], v[46:47], v[8:9] op_sel_hi:[0,1,1]
	v_lshlrev_b32_e32 v40, 16, v226
	v_and_b32_e32 v41, 0xffff0000, v226
	v_lshlrev_b32_e32 v42, 16, v227
	v_and_b32_e32 v43, 0xffff0000, v227
	v_lshlrev_b32_e32 v44, 16, v228
	v_and_b32_e32 v45, 0xffff0000, v228
	v_lshlrev_b32_e32 v46, 16, v229
	v_and_b32_e32 v47, 0xffff0000, v229
	v_pk_fma_f32 v[2:3], v[48:49], v[40:41], v[2:3] op_sel_hi:[0,1,1]
	v_pk_fma_f32 v[4:5], v[48:49], v[42:43], v[4:5] op_sel_hi:[0,1,1]
	v_pk_fma_f32 v[6:7], v[48:49], v[44:45], v[6:7] op_sel_hi:[0,1,1]
	v_pk_fma_f32 v[8:9], v[48:49], v[46:47], v[8:9] op_sel_hi:[0,1,1]
	v_mov_b32_e32 v1, v22
	v_div_scale_f32 v22, s[4:5], v1, v1, 1.0
	v_rcp_f32_e32 v23, v22
	s_nop 0
	v_fma_f32 v24, -v22, v23, 1.0
	v_div_scale_f32 v13, vcc, 1.0, v1, 1.0
	v_fmac_f32_e32 v23, v24, v23
	v_mul_f32_e32 v24, v13, v23
	v_fma_f32 v25, -v22, v24, v13
	v_fmac_f32_e32 v24, v25, v23
	v_fma_f32 v13, -v22, v24, v13
	v_div_fmas_f32 v13, v13, v23, v24
	v_div_fixup_f32 v22, v13, v1, 1.0
	v_pk_mul_f32 v[2:3], v[22:23], v[2:3] op_sel_hi:[0,1]
	v_pk_mul_f32 v[4:5], v[22:23], v[4:5] op_sel_hi:[0,1]
	v_pk_mul_f32 v[6:7], v[22:23], v[6:7] op_sel_hi:[0,1]
	v_pk_mul_f32 v[8:9], v[22:23], v[8:9] op_sel_hi:[0,1]
	v_cvt_pk_bf16_f32 v2, v2, v3
	v_cvt_pk_bf16_f32 v3, v4, v5
	v_cvt_pk_bf16_f32 v4, v6, v7
	v_cvt_pk_bf16_f32 v5, v8, v9
	global_store_dwordx4 v[230:231], v[2:5], off offset:1024

; DI unsigned xb_ld(unsigned* p)              { return __hip_atomic_load(p, __ATOMIC_RELAXED, __HIP_MEMORY_SCOPE_AGENT); }
; DI unsigned xb_add(unsigned* p, unsigned v) { return __hip_atomic_fetch_add(p, v, __ATOMIC_RELAXED, __HIP_MEMORY_SCOPE_AGENT); }
; #define XB_SPIN(cond, bar) do { unsigned _sp = 0; while (cond) { __builtin_amdgcn_s_sleep(1); \
;     if ((++_sp & 255u) == 0u) { if (xb_ld(&(bar)[XB_TMO])) break; if (_sp > XB_SPIN_CAP) { atomicAdd(&(bar)[XB_TMO], 1u); break; } } } } while (0)
; DI void xcd_barrier(const XcdBarrier& b) {
;     asm volatile("s_waitcnt vmcnt(0)" ::: "memory");
;     __syncthreads();
;     if (threadIdx.x == 0) {
;         unsigned* bar = b.bar;
;         __builtin_amdgcn_s_waitcnt(0);
;         unsigned nloc = b.st[0], nx = b.st[1];
;         if (nloc == 0u) { xcd_barrier_complete(bar, b.x, nloc, nx); b.st[0] = nloc; b.st[1] = nx; }
;         const unsigned old = xb_add(&bar[XB_XSUB(b.x)], 1u);
;         const unsigned gen = old / nloc;
;         if (old + 1u == (gen + 1u) * nloc) {
;             __builtin_amdgcn_fence(__ATOMIC_RELEASE, "agent");
;             asm volatile("s_waitcnt vmcnt(0)" ::: "memory");
;             const unsigned og = xb_add(&bar[XB_TOP], 1u);
;             const unsigned tg = og / nx;
;             if (og + 1u == (tg + 1u) * nx) xb_add(&bar[XB_TOPGEN], 1u);
;             else XB_SPIN(xb_ld(&bar[XB_TOPGEN]) == tg, bar);
;             __builtin_amdgcn_fence(__ATOMIC_ACQUIRE, "agent");
;             xb_add(&bar[XB_XGEN(b.x)], 1u);
;             asm volatile("s_waitcnt vmcnt(0)" ::: "memory");
;         } else {
;             XB_SPIN(xb_ld(&bar[XB_XGEN(b.x)]) == gen, bar);
;             __builtin_amdgcn_fence(__ATOMIC_ACQUIRE, "agent");
;             asm volatile("s_waitcnt vmcnt(0)" ::: "memory");
;         }
;     }
;     __syncthreads();
; }
; __global__ void __launch_bounds__(512, 1) k_mega(Params P) {
;     ...
;   phase5(P, smem); xcd_barrier(xb);
.LBB0_892:
	s_or_b64 exec, exec, s[10:11]
	s_cmp_eq_u32 s56, 1
	s_cbranch_scc0 .Lp5_end
	s_mov_b32 s56, 2
	s_branch .Lp5_glu
.Lp5_end:
	s_waitcnt vmcnt(0)
	s_barrier
	s_mov_b64 s[0:1], exec
	v_readlane_b32 s4, v254, 10
	v_readlane_b32 s5, v254, 11
	s_and_b64 s[4:5], s[0:1], s[4:5]
	s_mov_b64 exec, s[4:5]
	s_cbranch_execz .LBB0_944
	s_add_i32 s2, 0, 0x22a00
	v_mov_b32_e32 v0, s2
	s_waitcnt vmcnt(0) expcnt(0) lgkmcnt(0)
	ds_read_b32 v2, v0
	s_add_i32 s2, 0, 0x22a04
	v_mov_b32_e32 v0, s2
	ds_read_b32 v0, v0
	s_waitcnt lgkmcnt(1)
	v_cmp_ne_u32_e32 vcc, 0, v2
	s_cbranch_vccnz .LBB0_908
	v_readlane_b32 s4, v254, 8
	v_readlane_b32 s5, v254, 9
	s_mul_i32 s2, s5, s97
	s_mul_i32 s2, s2, s4
	s_add_u32 s4, s78, 0x18e00200
	s_addc_u32 s5, s79, 0
	s_add_u32 s6, s78, 0x18e00400
	s_addc_u32 s7, s79, 0
	s_add_u32 s10, s78, 0x18e00500
	s_addc_u32 s11, s79, 0
	s_add_u32 s12, s78, 0x18e00600
	s_addc_u32 s13, s79, 0
	s_add_u32 s14, s78, 0x18e00700
	s_addc_u32 s15, s79, 0
	s_add_u32 s16, s78, 0x18e00800
	s_addc_u32 s17, s79, 0
	s_add_u32 s18, s78, 0x18e00900
	s_addc_u32 s19, s79, 0
	s_add_u32 s20, s78, 0x18e00a00
	s_addc_u32 s21, s79, 0
	s_add_u32 s24, s78, 0x18e00b00
	s_addc_u32 s25, s79, 0
	s_add_u32 s28, s78, 0x18e00c00
	s_addc_u32 s29, s79, 0
	s_add_u32 s30, s78, 0x18e00d00
	s_addc_u32 s31, s79, 0
	s_add_u32 s34, s78, 0x18e00e00
	s_addc_u32 s35, s79, 0
	s_add_u32 s38, s78, 0x18e00f00
	s_addc_u32 s39, s79, 0
	s_add_u32 s42, s78, 0x18e01000
	s_addc_u32 s43, s79, 0
	s_add_u32 s48, s78, 0x18e01100
	s_addc_u32 s49, s79, 0
	s_add_u32 s26, s78, 0x18e01200
	s_addc_u32 s27, s79, 0
	s_add_u32 s8, s78, 0x18e01300
	s_addc_u32 s9, s79, 0
	s_mov_b32 s22, 1
	v_mov_b32_e32 v16, 0
	s_branch .LBB0_896
